# XCD barrier: last arriver of an XCD publishes the XCD generation word before issuing its acquire invalidate (11 of 12 sites)
# baseline (speedup 1.0000x reference)
.LBB0_87:
	s_or_b64 exec, exec, s[4:5]
	s_mov_b64 s[4:5], exec
	v_mbcnt_lo_u32_b32 v0, s4, 0
	v_mbcnt_hi_u32_b32 v0, s5, v0
	v_cmp_eq_u32_e32 vcc, 0, v0
	s_waitcnt vmcnt(0)
	s_and_saveexec_b64 s[8:9], vcc
	s_cbranch_execz .LBB0_89
	s_bcnt1_i32_b64 s3, s[4:5]
	v_mov_b32_e32 v0, 0x2000
	v_mov_b32_e32 v1, s3
	global_atomic_add v0, v1, s[6:7] offset:1024
.LBB0_89:
	s_or_b64 exec, exec, s[8:9]
	buffer_inv sc1
	s_waitcnt vmcnt(0)

.LBB0_631:
	s_or_b64 exec, exec, s[8:9]
	s_mov_b64 s[8:9], exec
	v_mbcnt_lo_u32_b32 v0, s8, 0
	v_mbcnt_hi_u32_b32 v0, s9, v0
	v_cmp_eq_u32_e32 vcc, 0, v0
	s_waitcnt vmcnt(0)
	s_and_saveexec_b64 s[12:13], vcc
	s_cbranch_execz .LBB0_633
	s_bcnt1_i32_b64 s0, s[8:9]
	v_mov_b32_e32 v0, s0
	global_atomic_add v218, v0, s[10:11] offset:1024
.LBB0_633:
	s_or_b64 exec, exec, s[12:13]
	buffer_inv sc1
	s_waitcnt vmcnt(0)

.LBB0_1306:
	s_or_b64 exec, exec, s[12:13]
	s_mov_b64 s[12:13], exec
	v_mbcnt_lo_u32_b32 v0, s12, 0
	v_mbcnt_hi_u32_b32 v0, s13, v0
	v_cmp_eq_u32_e32 vcc, 0, v0
	s_waitcnt vmcnt(0)
	s_and_saveexec_b64 s[16:17], vcc
	s_cbranch_execz .LBB0_1308
	s_bcnt1_i32_b64 s0, s[12:13]
	v_mov_b32_e32 v0, s0
	global_atomic_add v218, v0, s[14:15] offset:1024
.LBB0_1308:
	s_or_b64 exec, exec, s[16:17]
	buffer_inv sc1
	s_waitcnt vmcnt(0)
